# GLA chunk loop: decay and prefix-sum stages read all LDS fragments once and interleave the two tiles MFMAs
# speedup vs baseline: 1.0067x; 1.0067x over previous
; #define LAS __attribute__((address_space(3)))
; __device__ __forceinline__ unsigned cvt_pk_bf16(float lo, float hi) { const f32x2_t v = {lo, hi}; const bf16x2_t b = __builtin_convertvector(v, bf16x2_t); return __builtin_bit_cast(unsigned, b); }
; __device__ __forceinline__ float bf_lo(unsigned w) { return __uint_as_float(w << 16); }
; __device__ __forceinline__ float bf_hi(unsigned w) { return __uint_as_float(w & 0xffff0000u); }
; __device__ __forceinline__ float softplus_(float x) { return fmaxf(x, 0.f) + __logf(1.0f + __expf(-fabsf(x))); }
; #define LBAR() do { asm volatile("s_waitcnt lgkmcnt(0)" ::: "memory"); __builtin_amdgcn_s_barrier(); asm volatile("" ::: "memory"); } while (0)
; __device__ void gla_chunk_phase(const Params& p, int l, LAS unsigned char* lds) {
;     ...
;             for (int i = 0; i < 2; ++i) { const int id = wid + 8 * i, rt = id >> 2, ct = id & 3; const f32x4 z4 = {0.f, 0.f, 0.f, 0.f};
;                 const f32x4 z = mm_nt<1>(dnA, 40, rt * 16, upT, 40, ct * 16, r16, quad, z4);
;                 const int col = ct * 16 + r16; const float bz = bias_s[col];
;                 f32x4 la, lo;
; #pragma unroll
;                 for (int j = 0; j < 4; ++j) la[j] = -softplus_(-(z[j] + bz)) * (1.0f / 16.0f);
;                 const unsigned h01 = cvt_pk_bf16(la[0], la[1]), h23 = cvt_pk_bf16(la[2], la[3]);
;                 lo[0] = la[0] - bf_lo(h01); lo[1] = la[1] - bf_hi(h01); lo[2] = la[2] - bf_lo(h23); lo[3] = la[3] - bf_hi(h23);
;                 u32x2 hw; hw.x = h01; hw.y = h23; *(LAS u32x2*)(laT_hi + col * 72 + rt * 16 + quad * 4) = hw;
;                 st_bf4(laT_lo + col * 72 + rt * 16 + quad * 4, lo); }
;             LBAR();
; #pragma unroll
;             for (int i = 0; i < 2; ++i) { const int id = wid + 8 * i, rt = id >> 2, ct = id & 3; const f32x4 z4 = {0.f, 0.f, 0.f, 0.f};
;                 f32x4 acc = mm_nt<2>(Lm, 72, rt * 16, laT_hi, 72, ct * 16, r16, quad, z4);
;                 acc = mm_nt<2>(Lm, 72, rt * 16, laT_lo, 72, ct * 16, r16, quad, acc);
;                 const int col = ct * 16 + r16;
; #pragma unroll
;                 for (int j = 0; j < 4; ++j) b_s[(rt * 16 + quad * 4 + j) * 64 + col] = acc[j];
;                 if (rt == 3 && quad == 3) { tot_s[col] = acc[3]; dk_s[col] = __expf(acc[3]); } }
.LBB0_443:
	s_waitcnt lgkmcnt(0)
	s_barrier
	v_add_u32_e32 v42, v69, v83
	ds_read_b128 v[42:45], v42
	ds_read_b128 v[116:119], v70
	ds_read_b32 v53, v71
	ds_read_b128 v[204:207], v105
	s_waitcnt lgkmcnt(0)
	v_mfma_f32_16x16x32_bf16 v[42:45], v[42:45], v[116:119], 0
	v_mfma_f32_16x16x32_bf16 v[204:207], v[204:207], v[116:119], 0
	v_mov_b32_e32 v208, v53
	s_nop 7
	v_add_f32_e32 v62, v53, v42
	v_max_f32_e64 v42, -v62, 0
	v_mul_f32_e64 v62, |v62|, s97
	v_exp_f32_e32 v62, v62
	s_nop 0
	v_add_f32_e32 v62, 1.0, v62
	v_log_f32_e32 v62, v62
	s_nop 0
	v_mul_f32_e32 v63, 0x3f317217, v62
	v_fma_f32 v63, v62, s48, -v63
	v_fmac_f32_e32 v63, 0x3377d1cf, v62
	v_fmac_f32_e32 v63, 0x3f317217, v62
	v_mov_b32_e32 v62, v63
	v_add_f32_e32 v63, v53, v43
	v_max_f32_e64 v43, -v63, 0
	v_mul_f32_e64 v63, |v63|, s97
	v_exp_f32_e32 v63, v63
	s_nop 0
	v_add_f32_e32 v63, 1.0, v63
	v_log_f32_e32 v63, v63
	s_nop 0
	v_mul_f32_e32 v115, 0x3f317217, v63
	v_fma_f32 v115, v63, s48, -v115
	v_fmac_f32_e32 v115, 0x3377d1cf, v63
	v_fmac_f32_e32 v115, 0x3f317217, v63
	v_mov_b32_e32 v63, v115
	v_add_f32_e32 v115, v53, v44
	v_max_f32_e64 v44, -v115, 0
	v_mul_f32_e64 v115, |v115|, s97
	v_exp_f32_e32 v115, v115
	v_add_f32_e32 v53, v53, v45
	v_max_f32_e64 v45, -v53, 0
	v_mul_f32_e64 v53, |v53|, s97
	v_add_f32_e32 v115, 1.0, v115
	v_exp_f32_e32 v53, v53
	v_pk_add_f32 v[42:43], v[42:43], v[62:63]
	v_log_f32_e32 v115, v115
	v_add_f32_e32 v53, 1.0, v53
	v_pk_mul_f32 v[62:63], v[42:43], s[96:97] op_sel_hi:[1,0]
	v_mul_f32_e32 v116, 0x3f317217, v115
	v_fma_f32 v116, v115, s48, -v116
	v_fmac_f32_e32 v116, 0x3377d1cf, v115
	v_fmac_f32_e32 v116, 0x3f317217, v115
	v_cvt_pk_bf16_f32 v62, v62, v63
	v_lshlrev_b32_e32 v118, 16, v62
	v_mov_b32_e32 v115, v116
	v_mov_b32_e32 v116, v115
	v_and_b32_e32 v119, 0xffff0000, v62
	v_log_f32_e32 v53, v53
	v_pk_fma_f32 v[42:43], v[42:43], s[96:97], v[118:119] op_sel_hi:[1,0,1] neg_lo:[0,0,1] neg_hi:[0,0,1]
	v_mul_f32_e32 v115, 0x3f317217, v53
	v_fma_f32 v115, v53, s48, -v115
	v_fmac_f32_e32 v115, 0x3377d1cf, v53
	v_fmac_f32_e32 v115, 0x3f317217, v53
	v_cvt_pk_bf16_f32 v42, v42, v43
	s_nop 0
	v_mov_b32_e32 v53, v115
	v_mov_b32_e32 v117, v53
	v_pk_add_f32 v[44:45], v[44:45], v[116:117]
	s_nop 0
	v_pk_mul_f32 v[116:117], v[44:45], s[96:97] op_sel_hi:[1,0]
	s_nop 0
	v_cvt_pk_bf16_f32 v63, v116, v117
	v_lshlrev_b32_e32 v116, 16, v63
	v_and_b32_e32 v117, 0xffff0000, v63
	v_pk_fma_f32 v[44:45], v[44:45], s[96:97], v[116:117] op_sel_hi:[1,0,1] neg_lo:[0,0,1] neg_hi:[0,0,1]
	ds_write_b64 v84, v[62:63]
	v_cvt_pk_bf16_f32 v43, v44, v45
	ds_write_b64 v85, v[42:43]
	v_mov_b64_e32 v[42:43], v[204:205]
	v_mov_b64_e32 v[44:45], v[206:207]
	v_mov_b32_e32 v53, v208
	v_add_f32_e32 v62, v53, v42
	v_max_f32_e64 v42, -v62, 0
	v_mul_f32_e64 v62, |v62|, s97
	v_exp_f32_e32 v62, v62
	s_nop 0
	v_add_f32_e32 v62, 1.0, v62
	v_log_f32_e32 v62, v62
	s_nop 0
	v_mul_f32_e32 v63, 0x3f317217, v62
	v_fma_f32 v63, v62, s48, -v63
	v_fmac_f32_e32 v63, 0x3377d1cf, v62
	v_fmac_f32_e32 v63, 0x3f317217, v62
	v_mov_b32_e32 v62, v63
	v_add_f32_e32 v63, v53, v43
	v_max_f32_e64 v43, -v63, 0
	v_mul_f32_e64 v63, |v63|, s97
	v_exp_f32_e32 v63, v63
	s_nop 0
	v_add_f32_e32 v63, 1.0, v63
	v_log_f32_e32 v63, v63
	s_nop 0
	v_mul_f32_e32 v115, 0x3f317217, v63
	v_fma_f32 v115, v63, s48, -v115
	v_fmac_f32_e32 v115, 0x3377d1cf, v63
	v_fmac_f32_e32 v115, 0x3f317217, v63
	v_mov_b32_e32 v63, v115
	v_add_f32_e32 v115, v53, v44
	v_max_f32_e64 v44, -v115, 0
	v_mul_f32_e64 v115, |v115|, s97
	v_exp_f32_e32 v115, v115
	v_add_f32_e32 v53, v53, v45
	v_max_f32_e64 v45, -v53, 0
	v_mul_f32_e64 v53, |v53|, s97
	v_add_f32_e32 v115, 1.0, v115
	v_exp_f32_e32 v53, v53
	v_pk_add_f32 v[42:43], v[42:43], v[62:63]
	v_log_f32_e32 v115, v115
	v_add_f32_e32 v53, 1.0, v53
	v_pk_mul_f32 v[62:63], v[42:43], s[96:97] op_sel_hi:[1,0]
	v_mul_f32_e32 v116, 0x3f317217, v115
	v_fma_f32 v116, v115, s48, -v116
	v_fmac_f32_e32 v116, 0x3377d1cf, v115
	v_fmac_f32_e32 v116, 0x3f317217, v115
	v_cvt_pk_bf16_f32 v62, v62, v63
	v_lshlrev_b32_e32 v118, 16, v62
	v_mov_b32_e32 v115, v116
	v_mov_b32_e32 v116, v115
	v_and_b32_e32 v119, 0xffff0000, v62
	v_log_f32_e32 v53, v53
	v_pk_fma_f32 v[42:43], v[42:43], s[96:97], v[118:119] op_sel_hi:[1,0,1] neg_lo:[0,0,1] neg_hi:[0,0,1]
	v_mul_f32_e32 v115, 0x3f317217, v53
	v_fma_f32 v115, v53, s48, -v115
	v_fmac_f32_e32 v115, 0x3377d1cf, v53
	v_fmac_f32_e32 v115, 0x3f317217, v53
	v_cvt_pk_bf16_f32 v42, v42, v43
	s_nop 0
	v_mov_b32_e32 v53, v115
	v_mov_b32_e32 v117, v53
	v_pk_add_f32 v[44:45], v[44:45], v[116:117]
	v_add_u32_e32 v53, v72, v68
	v_pk_mul_f32 v[116:117], v[44:45], s[96:97] op_sel_hi:[1,0]
	s_nop 0
	v_cvt_pk_bf16_f32 v63, v116, v117
	v_lshlrev_b32_e32 v116, 16, v63
	v_and_b32_e32 v117, 0xffff0000, v63
	v_pk_fma_f32 v[44:45], v[44:45], s[96:97], v[116:117] op_sel_hi:[1,0,1] neg_lo:[0,0,1] neg_hi:[0,0,1]
	ds_write_b64 v84, v[62:63] offset:64
	v_cvt_pk_bf16_f32 v43, v44, v45
	ds_write_b64 v85, v[42:43] offset:64
	s_waitcnt lgkmcnt(0)
	s_barrier
	ds_read_b128 v[42:45], v106
	ds_read_b128 v[120:123], v106 offset:64
	ds_read_b128 v[180:183], v108
	ds_read_b128 v[184:187], v108 offset:64
	ds_read_b128 v[116:119], v53
	ds_read_b128 v[124:127], v53 offset:64
	v_add_u32_e32 v62, v73, v68
	ds_read_b128 v[188:191], v62
	ds_read_b128 v[192:195], v62 offset:64
	s_waitcnt lgkmcnt(0)
	v_mfma_f32_16x16x32_bf16 v[196:199], v[42:45], v[116:119], 0
	v_mfma_f32_16x16x32_bf16 v[200:203], v[180:183], v[116:119], 0
	v_mfma_f32_16x16x32_bf16 v[196:199], v[120:123], v[124:127], v[196:199]
	v_mfma_f32_16x16x32_bf16 v[200:203], v[184:187], v[124:127], v[200:203]
	v_mfma_f32_16x16x32_bf16 v[196:199], v[42:45], v[188:191], v[196:199]
	v_mfma_f32_16x16x32_bf16 v[200:203], v[180:183], v[188:191], v[200:203]
	v_mfma_f32_16x16x32_bf16 v[196:199], v[120:123], v[192:195], v[196:199]
	v_mfma_f32_16x16x32_bf16 v[200:203], v[184:187], v[192:195], v[200:203]
	s_nop 6
	ds_write2st64_b32 v107, v196, v197 offset1:1
	ds_write2st64_b32 v107, v198, v199 offset0:2 offset1:3
	s_and_saveexec_b64 s[20:21], s[88:89]
	s_cbranch_execz .LBB0_445
	v_mul_f32_e32 v42, 0x3fb8aa3b, v199
	v_exp_f32_e32 v42, v42
	ds_write_b32 v75, v199
	ds_write_b32 v74, v42
.LBB0_445:
	s_or_b64 exec, exec, s[20:21]
	ds_write2st64_b32 v109, v200, v201 offset1:1
	ds_write2st64_b32 v109, v202, v203 offset0:2 offset1:3
	s_and_saveexec_b64 s[20:21], s[90:91]
	s_cbranch_execz .LBB0_435
	v_mul_f32_e32 v42, 0x3fb8aa3b, v203
	v_exp_f32_e32 v42, v42
	ds_write_b32 v75, v203
	ds_write_b32 v74, v42
	s_branch .LBB0_435
